# attention unit output stage rewritten: lane-major private scratch (dwordx4 each way) and bf16 outputs transposed through LDS into dwordx4 stores
# speedup vs baseline: 1.0033x; 1.0033x over previous
; __device__ __forceinline__ void finishSM(f32x16& p0, f32x16& p1, float alpha, float& l_reg, bf16x8& pa0, bf16x8& pa1, bf16x8& pa2, bf16x8& pa3) {
; #pragma unroll
;   for (int r = 0; r < 16; ++r) p1[r] = __builtin_amdgcn_exp2f(p1[r]);
;   float ps = 0;
; #pragma unroll
;   for (int r = 0; r < 16; ++r) ps += p0[r];
; #pragma unroll
;   for (int r = 0; r < 16; ++r) ps += p1[r];
;   { auto rr = __builtin_amdgcn_permlane32_swap(__float_as_uint(ps), __float_as_uint(ps), false, false);
;     ps = __uint_as_float(rr[0]) + __uint_as_float(rr[1]); }
;   l_reg = l_reg * alpha + ps;
;     ...
;   PK4(p0, 0, pa0); PK4(p0, 8, pa1); PK4(p1, 0, pa2); PK4(p1, 8, pa3);
;     ...
; }
; __device__ __forceinline__ void qkt(f32x16& p0, f32x16& p1, const char* Ks, const bf16x8* qr, int r32, int hi, float m_ref) {
; #pragma unroll
;   for (int r = 0; r < 16; ++r) { p0[r] = -m_ref; p1[r] = -m_ref; }
; #pragma unroll
;   for (int d0 = 0; d0 < 4; ++d0) { const int cb = (d0 * 16 + hi * 8) * 2;
;     bf16x8 b0 = *reinterpret_cast<const bf16x8*>(Ks + KSWZ(r32, cb));
;     bf16x8 b1 = *reinterpret_cast<const bf16x8*>(Ks + KSWZ(32 + r32, cb));
;     p0 = __builtin_amdgcn_mfma_f32_32x32x16_bf16(b0, qr[d0], p0, 0, 0, 0);
;     p1 = __builtin_amdgcn_mfma_f32_32x32x16_bf16(b1, qr[d0], p1, 0, 0, 0); }
; }
; __device__ __forceinline__ int v_st(int k, int c) { const int kk = (k & ~0xC) | ((k & 4) << 1) | ((k & 8) >> 1); return ((kk >> 3) * 4 + (c >> 5)) * 512 + ((kk & 7) * 32 + (c & 31)) * 2; }
; __device__ __forceinline__ int v_rd_base(int lane) { return ((lane & 3) << 3) | (((lane >> 2) & 3) << 6) | (((lane >> 4) & 1) << 5) | (((lane >> 5) & 1) << 8); }
; template <int OFF> __device__ __forceinline__ s16x4 tr_read(int vb) {
;   s16x4 r; asm volatile("ds_read_b64_tr_b16 %0, %1 offset:%2" : "=&v"(r) : "v"(vb), "i"(OFF) : "memory"); return r;
; }
; template <int D0> __device__ __forceinline__ void pv_one(f32x16& od, int vb, bf16x8 pa0, bf16x8 pa1, bf16x8 pa2, bf16x8 pa3) {
;   const s16x4 l0 = tr_read<v_rd_off(D0, 0, 0)>(vb), h0 = tr_read<v_rd_off(D0, 0, 1)>(vb), l1 = tr_read<v_rd_off(D0, 1, 0)>(vb), h1 = tr_read<v_rd_off(D0, 1, 1)>(vb);
;   const s16x4 l2 = tr_read<v_rd_off(D0, 2, 0)>(vb), h2 = tr_read<v_rd_off(D0, 2, 1)>(vb), l3 = tr_read<v_rd_off(D0, 3, 0)>(vb), h3 = tr_read<v_rd_off(D0, 3, 1)>(vb);
;   asm volatile("s_waitcnt lgkmcnt(0)" ::: "memory"); SBAR();
.LBB0_1354:
	v_exp_f32_e32 v69, v96
	v_exp_f32_e32 v70, v97
	v_exp_f32_e32 v71, v98
	v_exp_f32_e32 v72, v99
	v_exp_f32_e32 v73, v100
	v_add_f32_e32 v67, 0, v69
	v_exp_f32_e32 v74, v101
	v_add_f32_e32 v67, v70, v67
	v_exp_f32_e32 v75, v102
	v_add_f32_e32 v67, v71, v67
	v_exp_f32_e32 v76, v103
	v_add_f32_e32 v67, v72, v67
	v_exp_f32_e32 v77, v104
	v_add_f32_e32 v67, v73, v67
	v_exp_f32_e32 v78, v105
	v_add_f32_e32 v67, v74, v67
	v_exp_f32_e32 v79, v106
	v_add_f32_e32 v67, v75, v67
	v_exp_f32_e32 v96, v107
	v_add_f32_e32 v67, v76, v67
	v_exp_f32_e32 v97, v108
	v_add_f32_e32 v67, v77, v67
	v_exp_f32_e32 v98, v109
	v_add_f32_e32 v67, v78, v67
	v_exp_f32_e32 v99, v110
	v_add_f32_e32 v67, v79, v67
	v_exp_f32_e32 v100, v111
	v_add_f32_e32 v67, v96, v67
	v_exp_f32_e32 v80, v80
	v_add_f32_e32 v67, v97, v67
	v_exp_f32_e32 v81, v81
	v_add_f32_e32 v67, v98, v67
	v_exp_f32_e32 v82, v82
	v_add_f32_e32 v67, v99, v67
	v_exp_f32_e32 v83, v83
	v_add_f32_e32 v67, v100, v67
	v_exp_f32_e32 v84, v84
	v_add_f32_e32 v67, v80, v67
	v_exp_f32_e32 v85, v85
	v_add_f32_e32 v67, v81, v67
	v_exp_f32_e32 v86, v86
	v_add_f32_e32 v67, v82, v67
	v_exp_f32_e32 v87, v87
	v_add_f32_e32 v67, v83, v67
	v_exp_f32_e32 v88, v88
	v_add_f32_e32 v67, v84, v67
	v_exp_f32_e32 v89, v89
	v_add_f32_e32 v67, v85, v67
	v_exp_f32_e32 v90, v90
	v_add_f32_e32 v67, v86, v67
	v_exp_f32_e32 v91, v91
	v_add_f32_e32 v67, v87, v67
	v_exp_f32_e32 v92, v92
	v_add_f32_e32 v67, v88, v67
	v_exp_f32_e32 v93, v93
	v_add_f32_e32 v67, v89, v67
	v_exp_f32_e32 v94, v94
	v_add_f32_e32 v67, v90, v67
	v_exp_f32_e32 v95, v95
	v_add_f32_e32 v67, v91, v67
	v_add_f32_e32 v67, v92, v67
	v_add_f32_e32 v67, v93, v67
	v_add_f32_e32 v67, v94, v67
	v_add_f32_e32 v67, v95, v67
	v_mov_b32_e32 v68, v67
	s_nop 1
	v_permlane32_swap_b32_e32 v67, v68
	v_cvt_pk_bf16_f32 v70, v69, v70
	v_cvt_pk_bf16_f32 v71, v71, v72
	v_cvt_pk_bf16_f32 v72, v73, v74
	v_cvt_pk_bf16_f32 v73, v75, v76
	v_cvt_pk_bf16_f32 v74, v77, v78
	v_cvt_pk_bf16_f32 v75, v79, v96
	v_cvt_pk_bf16_f32 v76, v97, v98
	v_cvt_pk_bf16_f32 v77, v99, v100
	v_cvt_pk_bf16_f32 v78, v80, v81
	v_cvt_pk_bf16_f32 v79, v82, v83
	v_cvt_pk_bf16_f32 v80, v84, v85
	v_cvt_pk_bf16_f32 v81, v86, v87
	v_cvt_pk_bf16_f32 v82, v88, v89
	v_cvt_pk_bf16_f32 v83, v90, v91
	v_cvt_pk_bf16_f32 v84, v92, v93
	v_cvt_pk_bf16_f32 v85, v94, v95
	s_nop 0
	s_nop 0
	s_nop 0
	s_nop 0
	s_nop 0
	s_nop 0
	s_nop 0
	s_nop 0
	s_nop 0
	ds_read_b64_tr_b16 v[86:87], v172 offset:0
	ds_read_b64_tr_b16 v[88:89], v172 offset:0x800
	ds_read_b64_tr_b16 v[90:91], v172 offset:0x1000
	ds_read_b64_tr_b16 v[92:93], v172 offset:0x1800
	ds_read_b64_tr_b16 v[94:95], v172 offset:0x2000
	ds_read_b64_tr_b16 v[96:97], v172 offset:0x2800
	ds_read_b64_tr_b16 v[98:99], v172 offset:0x3000
	ds_read_b64_tr_b16 v[100:101], v172 offset:0x3800
	s_waitcnt lgkmcnt(0)
	s_nop 0
	v_mfma_f32_32x32x16_bf16 v[0:15], v[70:73], v[86:89], v[0:15]
	ds_read_b64_tr_b16 v[86:87], v172 offset:0x200
	ds_read_b64_tr_b16 v[88:89], v172 offset:0xa00
	v_mfma_f32_32x32x16_bf16 v[0:15], v[74:77], v[90:93], v[0:15]
	ds_read_b64_tr_b16 v[90:91], v172 offset:0x1200
	ds_read_b64_tr_b16 v[92:93], v172 offset:0x1a00
	v_mfma_f32_32x32x16_bf16 v[0:15], v[78:81], v[94:97], v[0:15]
	ds_read_b64_tr_b16 v[94:95], v172 offset:0x2200
	ds_read_b64_tr_b16 v[96:97], v172 offset:0x2a00
	v_mfma_f32_32x32x16_bf16 v[0:15], v[82:85], v[98:101], v[0:15]
	ds_read_b64_tr_b16 v[98:99], v172 offset:0x3200
	ds_read_b64_tr_b16 v[100:101], v172 offset:0x3a00
	s_waitcnt lgkmcnt(0)
	v_mfma_f32_32x32x16_bf16 v[48:63], v[70:73], v[86:89], v[48:63]
	ds_read_b64_tr_b16 v[86:87], v172 offset:0x400
	ds_read_b64_tr_b16 v[88:89], v172 offset:0xc00
	v_mfma_f32_32x32x16_bf16 v[48:63], v[74:77], v[90:93], v[48:63]
	ds_read_b64_tr_b16 v[90:91], v172 offset:0x1400
	ds_read_b64_tr_b16 v[92:93], v172 offset:0x1c00
	v_mfma_f32_32x32x16_bf16 v[48:63], v[78:81], v[94:97], v[48:63]
	ds_read_b64_tr_b16 v[94:95], v172 offset:0x2400
	ds_read_b64_tr_b16 v[96:97], v172 offset:0x2c00
	v_mfma_f32_32x32x16_bf16 v[48:63], v[82:85], v[98:101], v[48:63]
	ds_read_b64_tr_b16 v[98:99], v172 offset:0x3400
	ds_read_b64_tr_b16 v[100:101], v172 offset:0x3c00
	s_waitcnt lgkmcnt(0)
	v_mfma_f32_32x32x16_bf16 v[32:47], v[70:73], v[86:89], v[32:47]
	ds_read_b64_tr_b16 v[86:87], v172 offset:0x600
	ds_read_b64_tr_b16 v[88:89], v172 offset:0xe00
	v_mfma_f32_32x32x16_bf16 v[32:47], v[74:77], v[90:93], v[32:47]
	ds_read_b64_tr_b16 v[90:91], v172 offset:0x1600
	ds_read_b64_tr_b16 v[92:93], v172 offset:0x1e00
	v_mfma_f32_32x32x16_bf16 v[32:47], v[78:81], v[94:97], v[32:47]
	ds_read_b64_tr_b16 v[94:95], v172 offset:0x2600
	ds_read_b64_tr_b16 v[96:97], v172 offset:0x2e00
	v_mfma_f32_32x32x16_bf16 v[32:47], v[82:85], v[98:101], v[32:47]
	ds_read_b64_tr_b16 v[98:99], v172 offset:0x3600
	ds_read_b64_tr_b16 v[100:101], v172 offset:0x3e00
	s_waitcnt lgkmcnt(0)
	v_mfma_f32_32x32x16_bf16 v[16:31], v[70:73], v[86:89], v[16:31]
	v_mfma_f32_32x32x16_bf16 v[16:31], v[74:77], v[90:93], v[16:31]
	v_mfma_f32_32x32x16_bf16 v[16:31], v[78:81], v[94:97], v[16:31]
	v_mfma_f32_32x32x16_bf16 v[16:31], v[82:85], v[98:101], v[16:31]
	s_setprio 0
	s_and_saveexec_b64 s[20:21], s[4:5]
	v_add_f32_e32 v64, v64, v65
	v_fmac_f32_e32 v64, v167, v158
	v_add_f32_e32 v65, v67, v68
	v_fmac_f32_e32 v65, v64, v66
	ds_write_b32 v153, v65
	s_or_b64 exec, exec, s[20:21]
	s_waitcnt lgkmcnt(0)
	v_lshl_add_u32 v64, v164, 4, v166
	ds_read_b128 v[68:71], v64
	ds_read_b128 v[72:75], v64 offset:32
	ds_read_b128 v[76:79], v64 offset:64
	ds_read_b128 v[80:83], v64 offset:96
	v_and_b32_e32 v65, 63, v214
	v_lshlrev_b32_e32 v66, 9, v152
	v_lshl_add_u32 v66, v65, 4, v66
	s_and_b64 vcc, exec, s[72:73]
	s_waitcnt lgkmcnt(0)
	v_rcp_f32_e32 v68, v68
	v_rcp_f32_e32 v69, v69
	v_rcp_f32_e32 v70, v70
	v_rcp_f32_e32 v71, v71
	v_rcp_f32_e32 v72, v72
	v_rcp_f32_e32 v73, v73
	v_rcp_f32_e32 v74, v74
	v_rcp_f32_e32 v75, v75
	v_rcp_f32_e32 v76, v76
	v_rcp_f32_e32 v77, v77
	v_rcp_f32_e32 v78, v78
	v_rcp_f32_e32 v79, v79
	v_rcp_f32_e32 v80, v80
	v_rcp_f32_e32 v81, v81
	v_rcp_f32_e32 v82, v82
	v_rcp_f32_e32 v83, v83
	s_cbranch_vccnz .Lat_mode1
; __device__ __forceinline__ int crow(int r, int hi) { return (r & 3) + 8 * (r >> 2) + 4 * hi; }
; __device__ __forceinline__ void attn_unit(const bf16_t* __restrict__ Qb, const bf16_t* __restrict__ Kh, const bf16_t* __restrict__ Vh, int seq, char* lds,
;                                           int mode, float* scratch, float lam, float gscale, const float* __restrict__ subg, bf16_t* outp) {
;     ...
;   if (mode == 0) {
; #pragma unroll
;     for (int r = 0; r < 16; ++r) { const int orow = crow(r, hi); const float rl = __builtin_amdgcn_rcpf(li_l[orow]);
; #pragma unroll
;       for (int d0 = 0; d0 < 4; ++d0) sw[orow * 128 + d0 * 32 + r32] = o[d0][r] * rl; }
;   } else {
;     bf16_t* ow = outp + (long)(wid * QBLK) * 1024;
;     float g4[4];
; #pragma unroll
;     for (int d0 = 0; d0 < 4; ++d0) g4[d0] = subg[d0 * 32 + r32] * gscale;
; #pragma unroll
;     for (int r = 0; r < 16; ++r) { const int orow = crow(r, hi); const float rl = __builtin_amdgcn_rcpf(li_l[orow]) * lam;
	v_mul_f32_e32 v84, v0, v68
	v_mul_f32_e32 v85, v48, v68
	v_mul_f32_e32 v86, v32, v68
	v_mul_f32_e32 v87, v16, v68
	global_store_dwordx4 v66, v[84:87], s[12:13] offset:0
	v_mul_f32_e32 v88, v1, v69
	v_mul_f32_e32 v89, v49, v69
	v_mul_f32_e32 v90, v33, v69
	v_mul_f32_e32 v91, v17, v69
	global_store_dwordx4 v66, v[88:91], s[12:13] offset:1024
	v_mul_f32_e32 v92, v2, v70
	v_mul_f32_e32 v93, v50, v70
	v_mul_f32_e32 v94, v34, v70
	v_mul_f32_e32 v95, v18, v70
	global_store_dwordx4 v66, v[92:95], s[12:13] offset:2048
	v_mul_f32_e32 v96, v3, v71
	v_mul_f32_e32 v97, v51, v71
	v_mul_f32_e32 v98, v35, v71
	v_mul_f32_e32 v99, v19, v71
	global_store_dwordx4 v66, v[96:99], s[12:13] offset:3072
	v_add_u32_e32 v66, 0x1000, v66
	v_mul_f32_e32 v84, v4, v72
	v_mul_f32_e32 v85, v52, v72
	v_mul_f32_e32 v86, v36, v72
	v_mul_f32_e32 v87, v20, v72
	global_store_dwordx4 v66, v[84:87], s[12:13] offset:0
	v_mul_f32_e32 v88, v5, v73
	v_mul_f32_e32 v89, v53, v73
	v_mul_f32_e32 v90, v37, v73
	v_mul_f32_e32 v91, v21, v73
	global_store_dwordx4 v66, v[88:91], s[12:13] offset:1024
	v_mul_f32_e32 v92, v6, v74
	v_mul_f32_e32 v93, v54, v74
	v_mul_f32_e32 v94, v38, v74
	v_mul_f32_e32 v95, v22, v74
	global_store_dwordx4 v66, v[92:95], s[12:13] offset:2048
	v_mul_f32_e32 v96, v7, v75
	v_mul_f32_e32 v97, v55, v75
	v_mul_f32_e32 v98, v39, v75
	v_mul_f32_e32 v99, v23, v75
	global_store_dwordx4 v66, v[96:99], s[12:13] offset:3072
	v_add_u32_e32 v66, 0x1000, v66
	v_mul_f32_e32 v84, v8, v76
	v_mul_f32_e32 v85, v56, v76
	v_mul_f32_e32 v86, v40, v76
	v_mul_f32_e32 v87, v24, v76
	global_store_dwordx4 v66, v[84:87], s[12:13] offset:0
	v_mul_f32_e32 v88, v9, v77
	v_mul_f32_e32 v89, v57, v77
	v_mul_f32_e32 v90, v41, v77
	v_mul_f32_e32 v91, v25, v77
	global_store_dwordx4 v66, v[88:91], s[12:13] offset:1024
	v_mul_f32_e32 v92, v10, v78
	v_mul_f32_e32 v93, v58, v78
	v_mul_f32_e32 v94, v42, v78
	v_mul_f32_e32 v95, v26, v78
	global_store_dwordx4 v66, v[92:95], s[12:13] offset:2048
	v_mul_f32_e32 v96, v11, v79
	v_mul_f32_e32 v97, v59, v79
	v_mul_f32_e32 v98, v43, v79
	v_mul_f32_e32 v99, v27, v79
	global_store_dwordx4 v66, v[96:99], s[12:13] offset:3072
	v_add_u32_e32 v66, 0x1000, v66
	v_mul_f32_e32 v84, v12, v80
	v_mul_f32_e32 v85, v60, v80
	v_mul_f32_e32 v86, v44, v80
	v_mul_f32_e32 v87, v28, v80
	global_store_dwordx4 v66, v[84:87], s[12:13] offset:0
	v_mul_f32_e32 v88, v13, v81
	v_mul_f32_e32 v89, v61, v81
	v_mul_f32_e32 v90, v45, v81
	v_mul_f32_e32 v91, v29, v81
	global_store_dwordx4 v66, v[88:91], s[12:13] offset:1024
	v_mul_f32_e32 v92, v14, v82
	v_mul_f32_e32 v93, v62, v82
	v_mul_f32_e32 v94, v46, v82
	v_mul_f32_e32 v95, v30, v82
	global_store_dwordx4 v66, v[92:95], s[12:13] offset:2048
	v_mul_f32_e32 v96, v15, v83
	v_mul_f32_e32 v97, v63, v83
	v_mul_f32_e32 v98, v47, v83
	v_mul_f32_e32 v99, v31, v83
	global_store_dwordx4 v66, v[96:99], s[12:13] offset:3072
	s_branch .LBB0_1328
.Lat_mode1:
	v_lshlrev_b32_e32 v67, 2, v165
	global_load_dword v84, v67, s[14:15]
	global_load_dword v85, v67, s[14:15] offset:128
	global_load_dword v86, v67, s[14:15] offset:256
	global_load_dword v87, v67, s[14:15] offset:384
	global_load_dwordx4 v[96:99], v66, s[12:13] offset:0
	global_load_dwordx4 v[100:103], v66, s[12:13] offset:1024
	global_load_dwordx4 v[104:107], v66, s[12:13] offset:2048
	global_load_dwordx4 v[108:111], v66, s[12:13] offset:3072
	v_add_u32_e32 v66, 0x1000, v66
	global_load_dwordx4 v[112:115], v66, s[12:13] offset:0
	global_load_dwordx4 v[116:119], v66, s[12:13] offset:1024
	global_load_dwordx4 v[120:123], v66, s[12:13] offset:2048
	global_load_dwordx4 v[124:127], v66, s[12:13] offset:3072
	v_add_u32_e32 v66, 0x1000, v66
	global_load_dwordx4 v[128:131], v66, s[12:13] offset:0
	global_load_dwordx4 v[132:135], v66, s[12:13] offset:1024
	global_load_dwordx4 v[136:139], v66, s[12:13] offset:2048
	global_load_dwordx4 v[140:143], v66, s[12:13] offset:3072
	v_add_u32_e32 v66, 0x1000, v66
	global_load_dwordx4 v[144:147], v66, s[12:13] offset:0
	global_load_dwordx4 v[148:151], v66, s[12:13] offset:1024
	global_load_dwordx4 v[182:185], v66, s[12:13] offset:2048
	global_load_dwordx4 v[186:189], v66, s[12:13] offset:3072
	v_mul_f32_e32 v68, v163, v68
	v_mul_f32_e32 v69, v163, v69
	v_mul_f32_e32 v70, v163, v70
	v_mul_f32_e32 v71, v163, v71
	v_mul_f32_e32 v72, v163, v72
	v_mul_f32_e32 v73, v163, v73
	v_mul_f32_e32 v74, v163, v74
	v_mul_f32_e32 v75, v163, v75
	v_mul_f32_e32 v76, v163, v76
	v_mul_f32_e32 v77, v163, v77
	v_mul_f32_e32 v78, v163, v78
	v_mul_f32_e32 v79, v163, v79
	v_mul_f32_e32 v80, v163, v80
	v_mul_f32_e32 v81, v163, v81
	v_mul_f32_e32 v82, v163, v82
	v_mul_f32_e32 v83, v163, v83
	v_mul_u32_u24_e32 v88, 136, v152
	v_add_u32_e32 v88, 0x15000, v88
	v_lshrrev_b32_e32 v89, 4, v65
	v_and_b32_e32 v90, 15, v65
	v_mul_u32_u24_e32 v91, 0x110, v89
	v_add_u32_e32 v91, v88, v91
	v_lshl_add_u32 v91, v90, 4, v91
	v_mul_u32_u24_e32 v92, 0x440, v164
	v_add_u32_e32 v88, v88, v92
	v_lshl_add_u32 v88, v165, 1, v88
	v_lshlrev_b32_e32 v92, 11, v152
	v_lshl_add_u32 v92, v89, 11, v92
	v_lshl_add_u32 v92, v90, 4, v92
	v_mov_b32_e32 v93, 0x3c000000
	v_mov_b32_e32 v94, 0x358637bd
	s_waitcnt vmcnt(16)
	v_mul_f32_e32 v84, v162, v84
	v_mul_f32_e32 v85, v162, v85
	v_mul_f32_e32 v86, v162, v86
	v_mul_f32_e32 v87, v162, v87
	s_waitcnt vmcnt(14)
; __device__ __forceinline__ unsigned f2bf(float f) { return pk2(f, 0.f) & 0xffffu; }
; __device__ __forceinline__ float sum32(float v) { return swap16_sum(sum16(v)); }
; __device__ __forceinline__ int crow(int r, int hi) { return (r & 3) + 8 * (r >> 2) + 4 * hi; }
; __device__ __forceinline__ void attn_unit(const bf16_t* __restrict__ Qb, const bf16_t* __restrict__ Kh, const bf16_t* __restrict__ Vh, int seq, char* lds,
;                                           int mode, float* scratch, float lam, float gscale, const float* __restrict__ subg, bf16_t* outp) {
;     ...
;     for (int r = 0; r < 16; ++r) { const int orow = crow(r, hi); const float rl = __builtin_amdgcn_rcpf(li_l[orow]) * lam;
;       float x[4]; float ss = 0.f;
; #pragma unroll
;       for (int d0 = 0; d0 < 4; ++d0) { x[d0] = sw[orow * 128 + d0 * 32 + r32] - o[d0][r] * rl; ss += x[d0] * x[d0]; }
;       ss = sum32(ss);
;       const float rn = rsqrtf(ss * (1.f / 128.f) + 1e-6f);
; #pragma unroll
;       for (int d0 = 0; d0 < 4; ++d0) ow[orow * 1024 + d0 * 32 + r32] = (bf16_t)f2bf(x[d0] * rn * g4[d0]); }
	v_fma_f32 v190, -v0, v68, v96
	v_fma_f32 v191, -v48, v68, v97
	v_fma_f32 v192, -v32, v68, v98
	v_fma_f32 v193, -v16, v68, v99
	v_fma_f32 v194, -v1, v69, v100
	v_fma_f32 v195, -v49, v69, v101
	v_fma_f32 v196, -v33, v69, v102
	v_fma_f32 v197, -v17, v69, v103
	v_mul_f32_e32 v198, v190, v190
	v_mul_f32_e32 v200, v191, v191
	v_mul_f32_e32 v199, v194, v194
	v_mul_f32_e32 v201, v195, v195
	v_add_f32_e32 v198, v198, v200
	v_add_f32_e32 v199, v199, v201
	v_mul_f32_e32 v200, v193, v193
	v_mul_f32_e32 v202, v192, v192
	v_mul_f32_e32 v201, v197, v197
	v_mul_f32_e32 v203, v196, v196
	v_add_f32_e32 v198, v200, v198
	v_add_f32_e32 v199, v201, v199
	v_add_f32_e32 v198, v202, v198
	v_add_f32_e32 v199, v203, v199
	s_nop 1
	v_add_f32_dpp v198, v198, v198 quad_perm:[1,0,3,2] row_mask:0xf bank_mask:0xf bound_ctrl:1
	v_add_f32_dpp v199, v199, v199 quad_perm:[1,0,3,2] row_mask:0xf bank_mask:0xf bound_ctrl:1
	s_nop 1
	v_add_f32_dpp v198, v198, v198 quad_perm:[2,3,0,1] row_mask:0xf bank_mask:0xf bound_ctrl:1
	v_add_f32_dpp v199, v199, v199 quad_perm:[2,3,0,1] row_mask:0xf bank_mask:0xf bound_ctrl:1
	s_nop 1
	v_add_f32_dpp v198, v198, v198 row_half_mirror row_mask:0xf bank_mask:0xf bound_ctrl:1
	v_add_f32_dpp v199, v199, v199 row_half_mirror row_mask:0xf bank_mask:0xf bound_ctrl:1
	s_nop 1
	v_add_f32_dpp v198, v198, v198 row_mirror row_mask:0xf bank_mask:0xf bound_ctrl:1
	v_add_f32_dpp v199, v199, v199 row_mirror row_mask:0xf bank_mask:0xf bound_ctrl:1
	v_mov_b32_e32 v200, v198
	v_mov_b32_e32 v201, v199
	s_nop 1
	v_permlane16_swap_b32_e32 v198, v200
	v_permlane16_swap_b32_e32 v199, v201
	v_add_f32_e32 v198, v198, v200
	v_add_f32_e32 v199, v199, v201
	v_fma_f32 v198, v198, v93, v94
	v_fma_f32 v199, v199, v93, v94
	v_rsq_f32_e32 v198, v198
	v_rsq_f32_e32 v199, v199
	s_nop 0
	v_mul_f32_e32 v190, v190, v198
	v_mul_f32_e32 v191, v191, v198
	v_mul_f32_e32 v192, v192, v198
	v_mul_f32_e32 v193, v193, v198
	v_mul_f32_e32 v190, v84, v190
	v_mul_f32_e32 v191, v85, v191
	v_mul_f32_e32 v192, v86, v192
	v_mul_f32_e32 v193, v87, v193
	v_cvt_pk_bf16_f32 v190, v190, v190
	v_cvt_pk_bf16_f32 v191, v191, v191
	v_cvt_pk_bf16_f32 v192, v192, v192
	v_cvt_pk_bf16_f32 v193, v193, v193
	ds_write_b16 v88, v190 offset:0
	ds_write_b16 v88, v191 offset:64
	ds_write_b16 v88, v192 offset:128
	ds_write_b16 v88, v193 offset:192
	v_mul_f32_e32 v194, v194, v199
	v_mul_f32_e32 v195, v195, v199
	v_mul_f32_e32 v196, v196, v199
	v_mul_f32_e32 v197, v197, v199
	v_mul_f32_e32 v194, v84, v194
	v_mul_f32_e32 v195, v85, v195
	v_mul_f32_e32 v196, v86, v196
	v_mul_f32_e32 v197, v87, v197
	v_cvt_pk_bf16_f32 v194, v194, v194
	v_cvt_pk_bf16_f32 v195, v195, v195
	v_cvt_pk_bf16_f32 v196, v196, v196
	v_cvt_pk_bf16_f32 v197, v197, v197
	ds_write_b16 v88, v194 offset:272
	ds_write_b16 v88, v195 offset:336
	ds_write_b16 v88, v196 offset:400
	ds_write_b16 v88, v197 offset:464
	s_waitcnt vmcnt(12)
	v_fma_f32 v190, -v2, v70, v104
	v_fma_f32 v191, -v50, v70, v105
	v_fma_f32 v192, -v34, v70, v106
	v_fma_f32 v193, -v18, v70, v107
	v_fma_f32 v194, -v3, v71, v108
	v_fma_f32 v195, -v51, v71, v109
	v_fma_f32 v196, -v35, v71, v110
	v_fma_f32 v197, -v19, v71, v111
	v_mul_f32_e32 v198, v190, v190
	v_mul_f32_e32 v200, v191, v191
	v_mul_f32_e32 v199, v194, v194
	v_mul_f32_e32 v201, v195, v195
	v_add_f32_e32 v198, v198, v200
	v_add_f32_e32 v199, v199, v201
	v_mul_f32_e32 v200, v193, v193
	v_mul_f32_e32 v202, v192, v192
	v_mul_f32_e32 v201, v197, v197
	v_mul_f32_e32 v203, v196, v196
	v_add_f32_e32 v198, v200, v198
	v_add_f32_e32 v199, v201, v199
	v_add_f32_e32 v198, v202, v198
	v_add_f32_e32 v199, v203, v199
	s_nop 1
	v_add_f32_dpp v198, v198, v198 quad_perm:[1,0,3,2] row_mask:0xf bank_mask:0xf bound_ctrl:1
	v_add_f32_dpp v199, v199, v199 quad_perm:[1,0,3,2] row_mask:0xf bank_mask:0xf bound_ctrl:1
	s_nop 1
	v_add_f32_dpp v198, v198, v198 quad_perm:[2,3,0,1] row_mask:0xf bank_mask:0xf bound_ctrl:1
	v_add_f32_dpp v199, v199, v199 quad_perm:[2,3,0,1] row_mask:0xf bank_mask:0xf bound_ctrl:1
	s_nop 1
	v_add_f32_dpp v198, v198, v198 row_half_mirror row_mask:0xf bank_mask:0xf bound_ctrl:1
	v_add_f32_dpp v199, v199, v199 row_half_mirror row_mask:0xf bank_mask:0xf bound_ctrl:1
	s_nop 1
	v_add_f32_dpp v198, v198, v198 row_mirror row_mask:0xf bank_mask:0xf bound_ctrl:1
	v_add_f32_dpp v199, v199, v199 row_mirror row_mask:0xf bank_mask:0xf bound_ctrl:1
	v_mov_b32_e32 v200, v198
	v_mov_b32_e32 v201, v199
	s_nop 1
	v_permlane16_swap_b32_e32 v198, v200
	v_permlane16_swap_b32_e32 v199, v201
	v_add_f32_e32 v198, v198, v200
	v_add_f32_e32 v199, v199, v201
	v_fma_f32 v198, v198, v93, v94
	v_fma_f32 v199, v199, v93, v94
	v_rsq_f32_e32 v198, v198
	v_rsq_f32_e32 v199, v199
	s_nop 0
	v_mul_f32_e32 v190, v190, v198
	v_mul_f32_e32 v191, v191, v198
	v_mul_f32_e32 v192, v192, v198
	v_mul_f32_e32 v193, v193, v198
	v_mul_f32_e32 v190, v84, v190
	v_mul_f32_e32 v191, v85, v191
	v_mul_f32_e32 v192, v86, v192
	v_mul_f32_e32 v193, v87, v193
	v_cvt_pk_bf16_f32 v190, v190, v190
	v_cvt_pk_bf16_f32 v191, v191, v191
	v_cvt_pk_bf16_f32 v192, v192, v192
	v_cvt_pk_bf16_f32 v193, v193, v193
	ds_write_b16 v88, v190 offset:544
	ds_write_b16 v88, v191 offset:608
	ds_write_b16 v88, v192 offset:672
	ds_write_b16 v88, v193 offset:736
	v_mul_f32_e32 v194, v194, v199
	v_mul_f32_e32 v195, v195, v199
	v_mul_f32_e32 v196, v196, v199
	v_mul_f32_e32 v197, v197, v199
	v_mul_f32_e32 v194, v84, v194
	v_mul_f32_e32 v195, v85, v195
	v_mul_f32_e32 v196, v86, v196
	v_mul_f32_e32 v197, v87, v197
	v_cvt_pk_bf16_f32 v194, v194, v194
	v_cvt_pk_bf16_f32 v195, v195, v195
	v_cvt_pk_bf16_f32 v196, v196, v196
	v_cvt_pk_bf16_f32 v197, v197, v197
	ds_write_b16 v88, v194 offset:816
	ds_write_b16 v88, v195 offset:880
	ds_write_b16 v88, v196 offset:944
	ds_write_b16 v88, v197 offset:1008
	s_waitcnt vmcnt(10)
; __device__ __forceinline__ unsigned f2bf(float f) { return pk2(f, 0.f) & 0xffffu; }
; __device__ __forceinline__ float sum32(float v) { return swap16_sum(sum16(v)); }
; __device__ __forceinline__ int crow(int r, int hi) { return (r & 3) + 8 * (r >> 2) + 4 * hi; }
; __device__ __forceinline__ void attn_unit(const bf16_t* __restrict__ Qb, const bf16_t* __restrict__ Kh, const bf16_t* __restrict__ Vh, int seq, char* lds,
;                                           int mode, float* scratch, float lam, float gscale, const float* __restrict__ subg, bf16_t* outp) {
;     ...
;     for (int r = 0; r < 16; ++r) { const int orow = crow(r, hi); const float rl = __builtin_amdgcn_rcpf(li_l[orow]) * lam;
;       float x[4]; float ss = 0.f;
; #pragma unroll
;       for (int d0 = 0; d0 < 4; ++d0) { x[d0] = sw[orow * 128 + d0 * 32 + r32] - o[d0][r] * rl; ss += x[d0] * x[d0]; }
;       ss = sum32(ss);
;       const float rn = rsqrtf(ss * (1.f / 128.f) + 1e-6f);
; #pragma unroll
;       for (int d0 = 0; d0 < 4; ++d0) ow[orow * 1024 + d0 * 32 + r32] = (bf16_t)f2bf(x[d0] * rn * g4[d0]); }
	v_fma_f32 v190, -v4, v72, v112
	v_fma_f32 v191, -v52, v72, v113
	v_fma_f32 v192, -v36, v72, v114
	v_fma_f32 v193, -v20, v72, v115
	v_fma_f32 v194, -v5, v73, v116
	v_fma_f32 v195, -v53, v73, v117
	v_fma_f32 v196, -v37, v73, v118
	v_fma_f32 v197, -v21, v73, v119
	v_mul_f32_e32 v198, v190, v190
	v_mul_f32_e32 v200, v191, v191
	v_mul_f32_e32 v199, v194, v194
	v_mul_f32_e32 v201, v195, v195
	v_add_f32_e32 v198, v198, v200
	v_add_f32_e32 v199, v199, v201
	v_mul_f32_e32 v200, v193, v193
	v_mul_f32_e32 v202, v192, v192
	v_mul_f32_e32 v201, v197, v197
	v_mul_f32_e32 v203, v196, v196
	v_add_f32_e32 v198, v200, v198
	v_add_f32_e32 v199, v201, v199
	v_add_f32_e32 v198, v202, v198
	v_add_f32_e32 v199, v203, v199
	s_nop 1
	v_add_f32_dpp v198, v198, v198 quad_perm:[1,0,3,2] row_mask:0xf bank_mask:0xf bound_ctrl:1
	v_add_f32_dpp v199, v199, v199 quad_perm:[1,0,3,2] row_mask:0xf bank_mask:0xf bound_ctrl:1
	s_nop 1
	v_add_f32_dpp v198, v198, v198 quad_perm:[2,3,0,1] row_mask:0xf bank_mask:0xf bound_ctrl:1
	v_add_f32_dpp v199, v199, v199 quad_perm:[2,3,0,1] row_mask:0xf bank_mask:0xf bound_ctrl:1
	s_nop 1
	v_add_f32_dpp v198, v198, v198 row_half_mirror row_mask:0xf bank_mask:0xf bound_ctrl:1
	v_add_f32_dpp v199, v199, v199 row_half_mirror row_mask:0xf bank_mask:0xf bound_ctrl:1
	s_nop 1
	v_add_f32_dpp v198, v198, v198 row_mirror row_mask:0xf bank_mask:0xf bound_ctrl:1
	v_add_f32_dpp v199, v199, v199 row_mirror row_mask:0xf bank_mask:0xf bound_ctrl:1
	v_mov_b32_e32 v200, v198
	v_mov_b32_e32 v201, v199
	s_nop 1
	v_permlane16_swap_b32_e32 v198, v200
	v_permlane16_swap_b32_e32 v199, v201
	v_add_f32_e32 v198, v198, v200
	v_add_f32_e32 v199, v199, v201
	v_fma_f32 v198, v198, v93, v94
	v_fma_f32 v199, v199, v93, v94
	v_rsq_f32_e32 v198, v198
	v_rsq_f32_e32 v199, v199
	s_nop 0
	v_mul_f32_e32 v190, v190, v198
	v_mul_f32_e32 v191, v191, v198
	v_mul_f32_e32 v192, v192, v198
	v_mul_f32_e32 v193, v193, v198
	v_mul_f32_e32 v190, v84, v190
	v_mul_f32_e32 v191, v85, v191
	v_mul_f32_e32 v192, v86, v192
	v_mul_f32_e32 v193, v87, v193
	v_cvt_pk_bf16_f32 v190, v190, v190
	v_cvt_pk_bf16_f32 v191, v191, v191
	v_cvt_pk_bf16_f32 v192, v192, v192
	v_cvt_pk_bf16_f32 v193, v193, v193
	ds_write_b16 v88, v190 offset:2176
	ds_write_b16 v88, v191 offset:2240
	ds_write_b16 v88, v192 offset:2304
	ds_write_b16 v88, v193 offset:2368
	v_mul_f32_e32 v194, v194, v199
	v_mul_f32_e32 v195, v195, v199
	v_mul_f32_e32 v196, v196, v199
	v_mul_f32_e32 v197, v197, v199
	v_mul_f32_e32 v194, v84, v194
	v_mul_f32_e32 v195, v85, v195
	v_mul_f32_e32 v196, v86, v196
	v_mul_f32_e32 v197, v87, v197
	v_cvt_pk_bf16_f32 v194, v194, v194
	v_cvt_pk_bf16_f32 v195, v195, v195
	v_cvt_pk_bf16_f32 v196, v196, v196
	v_cvt_pk_bf16_f32 v197, v197, v197
	ds_write_b16 v88, v194 offset:2448
	ds_write_b16 v88, v195 offset:2512
	ds_write_b16 v88, v196 offset:2576
	ds_write_b16 v88, v197 offset:2640
	s_waitcnt vmcnt(8)
	v_fma_f32 v190, -v6, v74, v120
	v_fma_f32 v191, -v54, v74, v121
	v_fma_f32 v192, -v38, v74, v122
	v_fma_f32 v193, -v22, v74, v123
	v_fma_f32 v194, -v7, v75, v124
	v_fma_f32 v195, -v55, v75, v125
	v_fma_f32 v196, -v39, v75, v126
	v_fma_f32 v197, -v23, v75, v127
	v_mul_f32_e32 v198, v190, v190
	v_mul_f32_e32 v200, v191, v191
	v_mul_f32_e32 v199, v194, v194
	v_mul_f32_e32 v201, v195, v195
	v_add_f32_e32 v198, v198, v200
	v_add_f32_e32 v199, v199, v201
	v_mul_f32_e32 v200, v193, v193
	v_mul_f32_e32 v202, v192, v192
	v_mul_f32_e32 v201, v197, v197
	v_mul_f32_e32 v203, v196, v196
	v_add_f32_e32 v198, v200, v198
	v_add_f32_e32 v199, v201, v199
	v_add_f32_e32 v198, v202, v198
	v_add_f32_e32 v199, v203, v199
	s_nop 1
	v_add_f32_dpp v198, v198, v198 quad_perm:[1,0,3,2] row_mask:0xf bank_mask:0xf bound_ctrl:1
	v_add_f32_dpp v199, v199, v199 quad_perm:[1,0,3,2] row_mask:0xf bank_mask:0xf bound_ctrl:1
	s_nop 1
	v_add_f32_dpp v198, v198, v198 quad_perm:[2,3,0,1] row_mask:0xf bank_mask:0xf bound_ctrl:1
	v_add_f32_dpp v199, v199, v199 quad_perm:[2,3,0,1] row_mask:0xf bank_mask:0xf bound_ctrl:1
	s_nop 1
	v_add_f32_dpp v198, v198, v198 row_half_mirror row_mask:0xf bank_mask:0xf bound_ctrl:1
	v_add_f32_dpp v199, v199, v199 row_half_mirror row_mask:0xf bank_mask:0xf bound_ctrl:1
	s_nop 1
	v_add_f32_dpp v198, v198, v198 row_mirror row_mask:0xf bank_mask:0xf bound_ctrl:1
	v_add_f32_dpp v199, v199, v199 row_mirror row_mask:0xf bank_mask:0xf bound_ctrl:1
	v_mov_b32_e32 v200, v198
	v_mov_b32_e32 v201, v199
	s_nop 1
	v_permlane16_swap_b32_e32 v198, v200
	v_permlane16_swap_b32_e32 v199, v201
	v_add_f32_e32 v198, v198, v200
	v_add_f32_e32 v199, v199, v201
	v_fma_f32 v198, v198, v93, v94
	v_fma_f32 v199, v199, v93, v94
	v_rsq_f32_e32 v198, v198
	v_rsq_f32_e32 v199, v199
	s_nop 0
	v_mul_f32_e32 v190, v190, v198
	v_mul_f32_e32 v191, v191, v198
	v_mul_f32_e32 v192, v192, v198
	v_mul_f32_e32 v193, v193, v198
	v_mul_f32_e32 v190, v84, v190
	v_mul_f32_e32 v191, v85, v191
	v_mul_f32_e32 v192, v86, v192
	v_mul_f32_e32 v193, v87, v193
	v_cvt_pk_bf16_f32 v190, v190, v190
	v_cvt_pk_bf16_f32 v191, v191, v191
	v_cvt_pk_bf16_f32 v192, v192, v192
	v_cvt_pk_bf16_f32 v193, v193, v193
	ds_write_b16 v88, v190 offset:2720
	ds_write_b16 v88, v191 offset:2784
	ds_write_b16 v88, v192 offset:2848
	ds_write_b16 v88, v193 offset:2912
	v_mul_f32_e32 v194, v194, v199
	v_mul_f32_e32 v195, v195, v199
	v_mul_f32_e32 v196, v196, v199
	v_mul_f32_e32 v197, v197, v199
	v_mul_f32_e32 v194, v84, v194
	v_mul_f32_e32 v195, v85, v195
	v_mul_f32_e32 v196, v86, v196
	v_mul_f32_e32 v197, v87, v197
	v_cvt_pk_bf16_f32 v194, v194, v194
	v_cvt_pk_bf16_f32 v195, v195, v195
	v_cvt_pk_bf16_f32 v196, v196, v196
	v_cvt_pk_bf16_f32 v197, v197, v197
	ds_write_b16 v88, v194 offset:2992
	ds_write_b16 v88, v195 offset:3056
	ds_write_b16 v88, v196 offset:3120
	ds_write_b16 v88, v197 offset:3184
	s_waitcnt lgkmcnt(0)
; __device__ __forceinline__ unsigned f2bf(float f) { return pk2(f, 0.f) & 0xffffu; }
; __device__ __forceinline__ float sum32(float v) { return swap16_sum(sum16(v)); }
; __device__ __forceinline__ int crow(int r, int hi) { return (r & 3) + 8 * (r >> 2) + 4 * hi; }
; __device__ __forceinline__ void attn_unit(const bf16_t* __restrict__ Qb, const bf16_t* __restrict__ Kh, const bf16_t* __restrict__ Vh, int seq, char* lds,
;                                           int mode, float* scratch, float lam, float gscale, const float* __restrict__ subg, bf16_t* outp) {
;     ...
;     for (int r = 0; r < 16; ++r) { const int orow = crow(r, hi); const float rl = __builtin_amdgcn_rcpf(li_l[orow]) * lam;
;       float x[4]; float ss = 0.f;
; #pragma unroll
;       for (int d0 = 0; d0 < 4; ++d0) { x[d0] = sw[orow * 128 + d0 * 32 + r32] - o[d0][r] * rl; ss += x[d0] * x[d0]; }
;       ss = sum32(ss);
;       const float rn = rsqrtf(ss * (1.f / 128.f) + 1e-6f);
; #pragma unroll
;       for (int d0 = 0; d0 < 4; ++d0) ow[orow * 1024 + d0 * 32 + r32] = (bf16_t)f2bf(x[d0] * rn * g4[d0]); }
	ds_read_b128 v[236:239], v91 offset:0
	ds_read_b128 v[240:243], v91 offset:1088
	ds_read_b128 v[244:247], v91 offset:2176
	ds_read_b128 v[248:251], v91 offset:3264
	s_waitcnt lgkmcnt(3)
	global_store_dwordx4 v92, v[236:239], s[22:23]
	v_add_u32_e32 v92, 0x2000, v92
	s_waitcnt lgkmcnt(2)
	global_store_dwordx4 v92, v[240:243], s[22:23]
	v_add_u32_e32 v92, 0x2000, v92
	s_waitcnt lgkmcnt(1)
	global_store_dwordx4 v92, v[244:247], s[22:23]
	v_add_u32_e32 v92, 0x2000, v92
	s_waitcnt lgkmcnt(0)
	global_store_dwordx4 v92, v[248:251], s[22:23]
	v_add_u32_e32 v92, 0x2000, v92
	s_waitcnt vmcnt(6)
	v_fma_f32 v190, -v8, v76, v128
	v_fma_f32 v191, -v56, v76, v129
	v_fma_f32 v192, -v40, v76, v130
	v_fma_f32 v193, -v24, v76, v131
	v_fma_f32 v194, -v9, v77, v132
	v_fma_f32 v195, -v57, v77, v133
	v_fma_f32 v196, -v41, v77, v134
	v_fma_f32 v197, -v25, v77, v135
	v_mul_f32_e32 v198, v190, v190
	v_mul_f32_e32 v200, v191, v191
	v_mul_f32_e32 v199, v194, v194
	v_mul_f32_e32 v201, v195, v195
	v_add_f32_e32 v198, v198, v200
	v_add_f32_e32 v199, v199, v201
	v_mul_f32_e32 v200, v193, v193
	v_mul_f32_e32 v202, v192, v192
	v_mul_f32_e32 v201, v197, v197
	v_mul_f32_e32 v203, v196, v196
	v_add_f32_e32 v198, v200, v198
	v_add_f32_e32 v199, v201, v199
	v_add_f32_e32 v198, v202, v198
	v_add_f32_e32 v199, v203, v199
	s_nop 1
	v_add_f32_dpp v198, v198, v198 quad_perm:[1,0,3,2] row_mask:0xf bank_mask:0xf bound_ctrl:1
	v_add_f32_dpp v199, v199, v199 quad_perm:[1,0,3,2] row_mask:0xf bank_mask:0xf bound_ctrl:1
	s_nop 1
	v_add_f32_dpp v198, v198, v198 quad_perm:[2,3,0,1] row_mask:0xf bank_mask:0xf bound_ctrl:1
	v_add_f32_dpp v199, v199, v199 quad_perm:[2,3,0,1] row_mask:0xf bank_mask:0xf bound_ctrl:1
	s_nop 1
	v_add_f32_dpp v198, v198, v198 row_half_mirror row_mask:0xf bank_mask:0xf bound_ctrl:1
	v_add_f32_dpp v199, v199, v199 row_half_mirror row_mask:0xf bank_mask:0xf bound_ctrl:1
	s_nop 1
	v_add_f32_dpp v198, v198, v198 row_mirror row_mask:0xf bank_mask:0xf bound_ctrl:1
	v_add_f32_dpp v199, v199, v199 row_mirror row_mask:0xf bank_mask:0xf bound_ctrl:1
	v_mov_b32_e32 v200, v198
	v_mov_b32_e32 v201, v199
	s_nop 1
	v_permlane16_swap_b32_e32 v198, v200
	v_permlane16_swap_b32_e32 v199, v201
	v_add_f32_e32 v198, v198, v200
	v_add_f32_e32 v199, v199, v201
	v_fma_f32 v198, v198, v93, v94
	v_fma_f32 v199, v199, v93, v94
	v_rsq_f32_e32 v198, v198
	v_rsq_f32_e32 v199, v199
	s_nop 0
	v_mul_f32_e32 v190, v190, v198
	v_mul_f32_e32 v191, v191, v198
	v_mul_f32_e32 v192, v192, v198
	v_mul_f32_e32 v193, v193, v198
	v_mul_f32_e32 v190, v84, v190
	v_mul_f32_e32 v191, v85, v191
	v_mul_f32_e32 v192, v86, v192
	v_mul_f32_e32 v193, v87, v193
	v_cvt_pk_bf16_f32 v190, v190, v190
	v_cvt_pk_bf16_f32 v191, v191, v191
	v_cvt_pk_bf16_f32 v192, v192, v192
	v_cvt_pk_bf16_f32 v193, v193, v193
	ds_write_b16 v88, v190 offset:0
	ds_write_b16 v88, v191 offset:64
	ds_write_b16 v88, v192 offset:128
	ds_write_b16 v88, v193 offset:192
	v_mul_f32_e32 v194, v194, v199
	v_mul_f32_e32 v195, v195, v199
	v_mul_f32_e32 v196, v196, v199
	v_mul_f32_e32 v197, v197, v199
	v_mul_f32_e32 v194, v84, v194
	v_mul_f32_e32 v195, v85, v195
	v_mul_f32_e32 v196, v86, v196
	v_mul_f32_e32 v197, v87, v197
	v_cvt_pk_bf16_f32 v194, v194, v194
	v_cvt_pk_bf16_f32 v195, v195, v195
	v_cvt_pk_bf16_f32 v196, v196, v196
	v_cvt_pk_bf16_f32 v197, v197, v197
	ds_write_b16 v88, v194 offset:272
	ds_write_b16 v88, v195 offset:336
	ds_write_b16 v88, v196 offset:400
	ds_write_b16 v88, v197 offset:464
	s_waitcnt vmcnt(4)
	v_fma_f32 v190, -v10, v78, v136
	v_fma_f32 v191, -v58, v78, v137
	v_fma_f32 v192, -v42, v78, v138
	v_fma_f32 v193, -v26, v78, v139
	v_fma_f32 v194, -v11, v79, v140
	v_fma_f32 v195, -v59, v79, v141
	v_fma_f32 v196, -v43, v79, v142
	v_fma_f32 v197, -v27, v79, v143
	v_mul_f32_e32 v198, v190, v190
	v_mul_f32_e32 v200, v191, v191
	v_mul_f32_e32 v199, v194, v194
	v_mul_f32_e32 v201, v195, v195
	v_add_f32_e32 v198, v198, v200
	v_add_f32_e32 v199, v199, v201
	v_mul_f32_e32 v200, v193, v193
	v_mul_f32_e32 v202, v192, v192
	v_mul_f32_e32 v201, v197, v197
	v_mul_f32_e32 v203, v196, v196
	v_add_f32_e32 v198, v200, v198
	v_add_f32_e32 v199, v201, v199
	v_add_f32_e32 v198, v202, v198
	v_add_f32_e32 v199, v203, v199
	s_nop 1
	v_add_f32_dpp v198, v198, v198 quad_perm:[1,0,3,2] row_mask:0xf bank_mask:0xf bound_ctrl:1
	v_add_f32_dpp v199, v199, v199 quad_perm:[1,0,3,2] row_mask:0xf bank_mask:0xf bound_ctrl:1
	s_nop 1
	v_add_f32_dpp v198, v198, v198 quad_perm:[2,3,0,1] row_mask:0xf bank_mask:0xf bound_ctrl:1
	v_add_f32_dpp v199, v199, v199 quad_perm:[2,3,0,1] row_mask:0xf bank_mask:0xf bound_ctrl:1
	s_nop 1
	v_add_f32_dpp v198, v198, v198 row_half_mirror row_mask:0xf bank_mask:0xf bound_ctrl:1
	v_add_f32_dpp v199, v199, v199 row_half_mirror row_mask:0xf bank_mask:0xf bound_ctrl:1
	s_nop 1
	v_add_f32_dpp v198, v198, v198 row_mirror row_mask:0xf bank_mask:0xf bound_ctrl:1
	v_add_f32_dpp v199, v199, v199 row_mirror row_mask:0xf bank_mask:0xf bound_ctrl:1
	v_mov_b32_e32 v200, v198
	v_mov_b32_e32 v201, v199
	s_nop 1
	v_permlane16_swap_b32_e32 v198, v200
	v_permlane16_swap_b32_e32 v199, v201
	v_add_f32_e32 v198, v198, v200
	v_add_f32_e32 v199, v199, v201
	v_fma_f32 v198, v198, v93, v94
	v_fma_f32 v199, v199, v93, v94
	v_rsq_f32_e32 v198, v198
	v_rsq_f32_e32 v199, v199
	s_nop 0
	v_mul_f32_e32 v190, v190, v198
	v_mul_f32_e32 v191, v191, v198
	v_mul_f32_e32 v192, v192, v198
	v_mul_f32_e32 v193, v193, v198
	v_mul_f32_e32 v190, v84, v190
	v_mul_f32_e32 v191, v85, v191
	v_mul_f32_e32 v192, v86, v192
	v_mul_f32_e32 v193, v87, v193
	v_cvt_pk_bf16_f32 v190, v190, v190
	v_cvt_pk_bf16_f32 v191, v191, v191
	v_cvt_pk_bf16_f32 v192, v192, v192
	v_cvt_pk_bf16_f32 v193, v193, v193
	ds_write_b16 v88, v190 offset:544
	ds_write_b16 v88, v191 offset:608
	ds_write_b16 v88, v192 offset:672
	ds_write_b16 v88, v193 offset:736
	v_mul_f32_e32 v194, v194, v199
	v_mul_f32_e32 v195, v195, v199
	v_mul_f32_e32 v196, v196, v199
	v_mul_f32_e32 v197, v197, v199
	v_mul_f32_e32 v194, v84, v194
	v_mul_f32_e32 v195, v85, v195
	v_mul_f32_e32 v196, v86, v196
	v_mul_f32_e32 v197, v87, v197
	v_cvt_pk_bf16_f32 v194, v194, v194
	v_cvt_pk_bf16_f32 v195, v195, v195
	v_cvt_pk_bf16_f32 v196, v196, v196
	v_cvt_pk_bf16_f32 v197, v197, v197
	ds_write_b16 v88, v194 offset:816
	ds_write_b16 v88, v195 offset:880
	ds_write_b16 v88, v196 offset:944
	ds_write_b16 v88, v197 offset:1008
	s_waitcnt vmcnt(2)
; __device__ __forceinline__ unsigned f2bf(float f) { return pk2(f, 0.f) & 0xffffu; }
; __device__ __forceinline__ float sum32(float v) { return swap16_sum(sum16(v)); }
; __device__ __forceinline__ int crow(int r, int hi) { return (r & 3) + 8 * (r >> 2) + 4 * hi; }
; __device__ __forceinline__ void attn_unit(const bf16_t* __restrict__ Qb, const bf16_t* __restrict__ Kh, const bf16_t* __restrict__ Vh, int seq, char* lds,
;                                           int mode, float* scratch, float lam, float gscale, const float* __restrict__ subg, bf16_t* outp) {
;     ...
;     for (int r = 0; r < 16; ++r) { const int orow = crow(r, hi); const float rl = __builtin_amdgcn_rcpf(li_l[orow]) * lam;
;       float x[4]; float ss = 0.f;
; #pragma unroll
;       for (int d0 = 0; d0 < 4; ++d0) { x[d0] = sw[orow * 128 + d0 * 32 + r32] - o[d0][r] * rl; ss += x[d0] * x[d0]; }
;       ss = sum32(ss);
;       const float rn = rsqrtf(ss * (1.f / 128.f) + 1e-6f);
; #pragma unroll
;       for (int d0 = 0; d0 < 4; ++d0) ow[orow * 1024 + d0 * 32 + r32] = (bf16_t)f2bf(x[d0] * rn * g4[d0]); }
	v_fma_f32 v190, -v12, v80, v144
	v_fma_f32 v191, -v60, v80, v145
	v_fma_f32 v192, -v44, v80, v146
	v_fma_f32 v193, -v28, v80, v147
	v_fma_f32 v194, -v13, v81, v148
	v_fma_f32 v195, -v61, v81, v149
	v_fma_f32 v196, -v45, v81, v150
	v_fma_f32 v197, -v29, v81, v151
	v_mul_f32_e32 v198, v190, v190
	v_mul_f32_e32 v200, v191, v191
	v_mul_f32_e32 v199, v194, v194
	v_mul_f32_e32 v201, v195, v195
	v_add_f32_e32 v198, v198, v200
	v_add_f32_e32 v199, v199, v201
	v_mul_f32_e32 v200, v193, v193
	v_mul_f32_e32 v202, v192, v192
	v_mul_f32_e32 v201, v197, v197
	v_mul_f32_e32 v203, v196, v196
	v_add_f32_e32 v198, v200, v198
	v_add_f32_e32 v199, v201, v199
	v_add_f32_e32 v198, v202, v198
	v_add_f32_e32 v199, v203, v199
	s_nop 1
	v_add_f32_dpp v198, v198, v198 quad_perm:[1,0,3,2] row_mask:0xf bank_mask:0xf bound_ctrl:1
	v_add_f32_dpp v199, v199, v199 quad_perm:[1,0,3,2] row_mask:0xf bank_mask:0xf bound_ctrl:1
	s_nop 1
	v_add_f32_dpp v198, v198, v198 quad_perm:[2,3,0,1] row_mask:0xf bank_mask:0xf bound_ctrl:1
	v_add_f32_dpp v199, v199, v199 quad_perm:[2,3,0,1] row_mask:0xf bank_mask:0xf bound_ctrl:1
	s_nop 1
	v_add_f32_dpp v198, v198, v198 row_half_mirror row_mask:0xf bank_mask:0xf bound_ctrl:1
	v_add_f32_dpp v199, v199, v199 row_half_mirror row_mask:0xf bank_mask:0xf bound_ctrl:1
	s_nop 1
	v_add_f32_dpp v198, v198, v198 row_mirror row_mask:0xf bank_mask:0xf bound_ctrl:1
	v_add_f32_dpp v199, v199, v199 row_mirror row_mask:0xf bank_mask:0xf bound_ctrl:1
	v_mov_b32_e32 v200, v198
	v_mov_b32_e32 v201, v199
	s_nop 1
	v_permlane16_swap_b32_e32 v198, v200
	v_permlane16_swap_b32_e32 v199, v201
	v_add_f32_e32 v198, v198, v200
	v_add_f32_e32 v199, v199, v201
	v_fma_f32 v198, v198, v93, v94
	v_fma_f32 v199, v199, v93, v94
	v_rsq_f32_e32 v198, v198
	v_rsq_f32_e32 v199, v199
	s_nop 0
	v_mul_f32_e32 v190, v190, v198
	v_mul_f32_e32 v191, v191, v198
	v_mul_f32_e32 v192, v192, v198
	v_mul_f32_e32 v193, v193, v198
	v_mul_f32_e32 v190, v84, v190
	v_mul_f32_e32 v191, v85, v191
	v_mul_f32_e32 v192, v86, v192
	v_mul_f32_e32 v193, v87, v193
	v_cvt_pk_bf16_f32 v190, v190, v190
	v_cvt_pk_bf16_f32 v191, v191, v191
	v_cvt_pk_bf16_f32 v192, v192, v192
	v_cvt_pk_bf16_f32 v193, v193, v193
	ds_write_b16 v88, v190 offset:2176
	ds_write_b16 v88, v191 offset:2240
	ds_write_b16 v88, v192 offset:2304
	ds_write_b16 v88, v193 offset:2368
	v_mul_f32_e32 v194, v194, v199
	v_mul_f32_e32 v195, v195, v199
	v_mul_f32_e32 v196, v196, v199
	v_mul_f32_e32 v197, v197, v199
	v_mul_f32_e32 v194, v84, v194
	v_mul_f32_e32 v195, v85, v195
	v_mul_f32_e32 v196, v86, v196
	v_mul_f32_e32 v197, v87, v197
	v_cvt_pk_bf16_f32 v194, v194, v194
	v_cvt_pk_bf16_f32 v195, v195, v195
	v_cvt_pk_bf16_f32 v196, v196, v196
	v_cvt_pk_bf16_f32 v197, v197, v197
	ds_write_b16 v88, v194 offset:2448
	ds_write_b16 v88, v195 offset:2512
	ds_write_b16 v88, v196 offset:2576
	ds_write_b16 v88, v197 offset:2640
	s_waitcnt vmcnt(0)
	v_fma_f32 v190, -v14, v82, v182
	v_fma_f32 v191, -v62, v82, v183
	v_fma_f32 v192, -v46, v82, v184
	v_fma_f32 v193, -v30, v82, v185
	v_fma_f32 v194, -v15, v83, v186
	v_fma_f32 v195, -v63, v83, v187
	v_fma_f32 v196, -v47, v83, v188
	v_fma_f32 v197, -v31, v83, v189
	v_mul_f32_e32 v198, v190, v190
	v_mul_f32_e32 v200, v191, v191
	v_mul_f32_e32 v199, v194, v194
	v_mul_f32_e32 v201, v195, v195
	v_add_f32_e32 v198, v198, v200
	v_add_f32_e32 v199, v199, v201
	v_mul_f32_e32 v200, v193, v193
	v_mul_f32_e32 v202, v192, v192
	v_mul_f32_e32 v201, v197, v197
	v_mul_f32_e32 v203, v196, v196
	v_add_f32_e32 v198, v200, v198
	v_add_f32_e32 v199, v201, v199
	v_add_f32_e32 v198, v202, v198
	v_add_f32_e32 v199, v203, v199
	s_nop 1
	v_add_f32_dpp v198, v198, v198 quad_perm:[1,0,3,2] row_mask:0xf bank_mask:0xf bound_ctrl:1
	v_add_f32_dpp v199, v199, v199 quad_perm:[1,0,3,2] row_mask:0xf bank_mask:0xf bound_ctrl:1
	s_nop 1
	v_add_f32_dpp v198, v198, v198 quad_perm:[2,3,0,1] row_mask:0xf bank_mask:0xf bound_ctrl:1
	v_add_f32_dpp v199, v199, v199 quad_perm:[2,3,0,1] row_mask:0xf bank_mask:0xf bound_ctrl:1
	s_nop 1
	v_add_f32_dpp v198, v198, v198 row_half_mirror row_mask:0xf bank_mask:0xf bound_ctrl:1
	v_add_f32_dpp v199, v199, v199 row_half_mirror row_mask:0xf bank_mask:0xf bound_ctrl:1
	s_nop 1
	v_add_f32_dpp v198, v198, v198 row_mirror row_mask:0xf bank_mask:0xf bound_ctrl:1
	v_add_f32_dpp v199, v199, v199 row_mirror row_mask:0xf bank_mask:0xf bound_ctrl:1
	v_mov_b32_e32 v200, v198
	v_mov_b32_e32 v201, v199
	s_nop 1
	v_permlane16_swap_b32_e32 v198, v200
	v_permlane16_swap_b32_e32 v199, v201
	v_add_f32_e32 v198, v198, v200
	v_add_f32_e32 v199, v199, v201
	v_fma_f32 v198, v198, v93, v94
	v_fma_f32 v199, v199, v93, v94
	v_rsq_f32_e32 v198, v198
	v_rsq_f32_e32 v199, v199
	s_nop 0
	v_mul_f32_e32 v190, v190, v198
	v_mul_f32_e32 v191, v191, v198
	v_mul_f32_e32 v192, v192, v198
	v_mul_f32_e32 v193, v193, v198
	v_mul_f32_e32 v190, v84, v190
	v_mul_f32_e32 v191, v85, v191
	v_mul_f32_e32 v192, v86, v192
	v_mul_f32_e32 v193, v87, v193
	v_cvt_pk_bf16_f32 v190, v190, v190
	v_cvt_pk_bf16_f32 v191, v191, v191
	v_cvt_pk_bf16_f32 v192, v192, v192
	v_cvt_pk_bf16_f32 v193, v193, v193
	ds_write_b16 v88, v190 offset:2720
	ds_write_b16 v88, v191 offset:2784
	ds_write_b16 v88, v192 offset:2848
	ds_write_b16 v88, v193 offset:2912
	v_mul_f32_e32 v194, v194, v199
	v_mul_f32_e32 v195, v195, v199
	v_mul_f32_e32 v196, v196, v199
	v_mul_f32_e32 v197, v197, v199
	v_mul_f32_e32 v194, v84, v194
	v_mul_f32_e32 v195, v85, v195
	v_mul_f32_e32 v196, v86, v196
	v_mul_f32_e32 v197, v87, v197
	v_cvt_pk_bf16_f32 v194, v194, v194
	v_cvt_pk_bf16_f32 v195, v195, v195
	v_cvt_pk_bf16_f32 v196, v196, v196
	v_cvt_pk_bf16_f32 v197, v197, v197
	ds_write_b16 v88, v194 offset:2992
	ds_write_b16 v88, v195 offset:3056
	ds_write_b16 v88, v196 offset:3120
	ds_write_b16 v88, v197 offset:3184
	s_waitcnt lgkmcnt(0)
	ds_read_b128 v[236:239], v91 offset:0
	ds_read_b128 v[240:243], v91 offset:1088
	ds_read_b128 v[244:247], v91 offset:2176
	ds_read_b128 v[248:251], v91 offset:3264
	s_waitcnt lgkmcnt(3)
	global_store_dwordx4 v92, v[236:239], s[22:23]
	v_add_u32_e32 v92, 0x2000, v92
	s_waitcnt lgkmcnt(2)
	global_store_dwordx4 v92, v[240:243], s[22:23]
	v_add_u32_e32 v92, 0x2000, v92
	s_waitcnt lgkmcnt(1)
	global_store_dwordx4 v92, v[244:247], s[22:23]
	v_add_u32_e32 v92, 0x2000, v92
	s_waitcnt lgkmcnt(0)
	global_store_dwordx4 v92, v[248:251], s[22:23]
	v_add_u32_e32 v92, 0x2000, v92
	s_branch .LBB0_1328
